# v32: v31 + out-proj fused epilogue weight/scale/shift vector loads issued together (one wait instead of five)
# speedup vs baseline: 1.0075x; 1.0075x over previous
; __device__ __forceinline__ unsigned cvt_pk_bf16(float lo, float hi) { const f32x2 v = {lo, hi}; const bf16x2_t b = __builtin_convertvector(v, bf16x2_t); return __builtin_bit_cast(unsigned, b); }
;     __device__ __forceinline__ void fused(f32x4 (&acc)[2][2][4][2], const Unit& u, int wr, int wc, int fr, int fq, LAS unsigned char* lds, int wid, int lane) const {
;     ...
;         {
;             f32x4 Av[2][2], Bv[2][2];
; #pragma unroll
;             for (int bj = 0; bj < 2; ++bj)
; #pragma unroll
;                 for (int n = 0; n < 2; ++n) {
;                     const int c = col0 + bj * 128 + n * 16;
;                     Av[bj][n] = *(const f32x4*)(gw + c); Bv[bj][n] = (f32x4){0.f, 0.f, 0.f, 0.f};
;                     if (mode == 0) { Av[bj][n] = Av[bj][n] * (*(const f32x4*)(sc + (size_t)bb * ADAW + c) + 1.0f); Bv[bj][n] = *(const f32x4*)(sh + (size_t)bb * ADAW + c); }
;                 }
; #pragma unroll
;             for (int ai = 0; ai < 2; ++ai)
; #pragma unroll
;                 for (int m = 0; m < 4; ++m) {
;                     const int r = ai * 128 + wr * 64 + m * 16 + fr; const float rinv = S[r];
;                     const size_t off = (size_t)(u.pm * 256 + r) * DM + col0;
; #pragma unroll
;                     for (int bj = 0; bj < 2; ++bj)
; #pragma unroll
;                         for (int n = 0; n < 2; ++n) {
;                             const f32x4 y = acc[ai][bj][m][n] * rinv * Av[bj][n] + Bv[bj][n];
;                             if (mode == 0) { u32x2 w; w.x = cvt_pk_bf16(y[0], y[1]); w.y = cvt_pk_bf16(y[2], y[3]); *(u32x2*)(H + off + bj * 128 + n * 16) = w; }
;                             else *(f32x4*)(Fout + off + bj * 128 + n * 16) = y;
;                         }
.LBB0_815:
	s_or_b64 exec, exec, s[2:3]
	s_mov_b32 s3, s25
	v_writelane_b32 v251, s2, 23
	s_lshl_b32 s24, s80, 11
	s_waitcnt vmcnt(0) lgkmcnt(0)
	s_barrier
	v_writelane_b32 v251, s3, 24
	s_lshl_b64 s[2:3], s[24:25], 2
	v_readlane_b32 s16, v251, 5
	v_readlane_b32 s26, v251, 15
	v_readlane_b32 s27, v251, 16
	s_mov_b64 s[14:15], s[26:27]
	s_add_u32 s2, s14, s2
	s_addc_u32 s3, s15, s3
	s_add_u32 s6, s34, s12
	s_addc_u32 s7, s35, s13
	v_lshl_add_u64 v[138:139], s[6:7], 0, v[160:161]
	v_add_co_u32_e32 v134, vcc, s77, v138
	v_lshl_add_u64 v[162:163], s[2:3], 0, v[160:161]
	s_nop 0
	v_addc_co_u32_e32 v135, vcc, 0, v139, vcc
	global_load_dwordx4 v[184:187], v[134:135], off
	s_movk_i32 s0, 0x6000
	global_load_dwordx4 v[168:171], v[162:163], off
	s_mov_b64 s[2:3], 0x8000
	v_lshl_add_u64 v[160:161], v[138:139], 0, s[2:3]
	s_mov_b64 s[2:3], 0x6000
	v_lshl_add_u64 v[164:165], v[138:139], 0, s[2:3]
	global_load_dwordx4 v[172:175], v[162:163], off offset:64
	global_load_dwordx4 v[188:191], v[160:161], off offset:64
	global_load_dwordx4 v[176:179], v[162:163], off offset:512
	global_load_dwordx4 v[192:195], v[160:161], off offset:512
	global_load_dwordx4 v[180:183], v[162:163], off offset:576
	global_load_dwordx4 v[196:199], v[160:161], off offset:576
	global_load_dwordx4 v[130:133], v[164:165], off
	global_load_dwordx4 v[134:137], v[164:165], off offset:64
	global_load_dwordx4 v[138:141], v[164:165], off offset:512
	global_load_dwordx4 v[142:145], v[164:165], off offset:576
	v_readlane_b32 s17, v251, 6
	v_readlane_b32 s18, v251, 7
	v_readlane_b32 s19, v251, 8
	v_readlane_b32 s20, v251, 9
	v_readlane_b32 s21, v251, 10
	v_readlane_b32 s22, v251, 11
	v_readlane_b32 s23, v251, 12
	v_readlane_b32 s24, v251, 13
	v_readlane_b32 s25, v251, 14
	v_readlane_b32 s28, v251, 17
	v_readlane_b32 s29, v251, 18
	v_readlane_b32 s30, v251, 19
	v_readlane_b32 s31, v251, 20
	s_waitcnt vmcnt(4)
	v_pk_add_f32 v[184:185], v[184:185], 1.0 op_sel_hi:[1,0]
	v_pk_add_f32 v[186:187], v[186:187], 1.0 op_sel_hi:[1,0]
	v_pk_add_f32 v[188:189], v[188:189], 1.0 op_sel_hi:[1,0]
	v_pk_add_f32 v[190:191], v[190:191], 1.0 op_sel_hi:[1,0]
	v_pk_add_f32 v[192:193], v[192:193], 1.0 op_sel_hi:[1,0]
	v_pk_add_f32 v[194:195], v[194:195], 1.0 op_sel_hi:[1,0]
	v_pk_add_f32 v[196:197], v[196:197], 1.0 op_sel_hi:[1,0]
	v_pk_add_f32 v[198:199], v[198:199], 1.0 op_sel_hi:[1,0]
	v_pk_mul_f32 v[148:149], v[168:169], v[184:185]
	v_pk_mul_f32 v[146:147], v[170:171], v[186:187]
	v_pk_mul_f32 v[152:153], v[172:173], v[188:189]
	v_pk_mul_f32 v[150:151], v[174:175], v[190:191]
	v_pk_mul_f32 v[156:157], v[176:177], v[192:193]
	v_pk_mul_f32 v[154:155], v[178:179], v[194:195]
	v_pk_mul_f32 v[162:163], v[180:181], v[196:197]
	v_pk_mul_f32 v[160:161], v[182:183], v[198:199]
	s_waitcnt vmcnt(1)
	v_lshl_add_u32 v164, v0, 2, 0
	v_add_u32_e32 v168, 0x1000, v164
	ds_read2_b32 v[166:167], v168 offset1:16
	v_add_u32_e32 v164, s1, v0
	v_ashrrev_i32_e32 v165, 31, v164
	v_readlane_b32 s0, v253, 52
	v_readlane_b32 s1, v253, 53
	s_waitcnt lgkmcnt(0)
	v_pk_mul_f32 v[126:127], v[126:127], v[166:167] op_sel_hi:[1,0]
	v_pk_mul_f32 v[128:129], v[128:129], v[166:167] op_sel_hi:[1,0]
	v_pk_fma_f32 v[126:127], v[148:149], v[126:127], v[130:131]
	v_pk_fma_f32 v[128:129], v[146:147], v[128:129], v[132:133]
	v_cvt_pk_bf16_f32 v170, v126, v127
	v_lshlrev_b64 v[126:127], 12, v[164:165]
	v_pk_mul_f32 v[114:115], v[114:115], v[166:167] op_sel_hi:[1,0]
	v_pk_mul_f32 v[116:117], v[116:117], v[166:167] op_sel_hi:[1,0]
	v_cvt_pk_bf16_f32 v171, v128, v129
	v_lshl_add_u64 v[128:129], s[0:1], 0, v[126:127]
	v_lshlrev_b64 v[126:127], 1, v[158:159]
	v_pk_fma_f32 v[116:117], v[150:151], v[116:117], v[136:137]
	v_pk_fma_f32 v[114:115], v[152:153], v[114:115], v[134:135]
	v_lshl_add_u64 v[128:129], v[128:129], 0, v[126:127]
	v_cvt_pk_bf16_f32 v114, v114, v115
	v_cvt_pk_bf16_f32 v115, v116, v117
	global_store_dwordx2 v[128:129], v[114:115], off offset:32
	v_pk_mul_f32 v[114:115], v[122:123], v[166:167] op_sel_hi:[1,0]
	v_pk_mul_f32 v[116:117], v[124:125], v[166:167] op_sel_hi:[1,0]
	v_pk_fma_f32 v[114:115], v[156:157], v[114:115], v[138:139]
	v_pk_fma_f32 v[116:117], v[154:155], v[116:117], v[140:141]
	v_cvt_pk_bf16_f32 v114, v114, v115
	v_cvt_pk_bf16_f32 v115, v116, v117
	global_store_dwordx2 v[128:129], v[114:115], off offset:256
	v_pk_mul_f32 v[114:115], v[118:119], v[166:167] op_sel_hi:[1,0]
	v_pk_mul_f32 v[116:117], v[120:121], v[166:167] op_sel_hi:[1,0]
	v_mov_b32_e32 v0, v167
	v_pk_mul_f32 v[110:111], v[110:111], v[0:1] op_sel_hi:[1,0]
	v_pk_mul_f32 v[112:113], v[112:113], v[0:1] op_sel_hi:[1,0]
	v_pk_fma_f32 v[110:111], v[148:149], v[110:111], v[130:131]
	v_pk_fma_f32 v[112:113], v[146:147], v[112:113], v[132:133]
	v_cvt_pk_bf16_f32 v110, v110, v111
	v_cvt_pk_bf16_f32 v111, v112, v113
	v_pk_mul_f32 v[18:19], v[18:19], v[0:1] op_sel_hi:[1,0]
	v_pk_mul_f32 v[20:21], v[20:21], v[0:1] op_sel_hi:[1,0]
	v_pk_fma_f32 v[18:19], v[152:153], v[18:19], v[134:135]
	v_pk_fma_f32 v[20:21], v[150:151], v[20:21], v[136:137]
	v_cvt_pk_bf16_f32 v18, v18, v19
	v_cvt_pk_bf16_f32 v19, v20, v21
	v_pk_mul_f32 v[20:21], v[24:25], v[0:1] op_sel_hi:[1,0]
	global_store_dwordx2 v[128:129], v[170:171], off
	v_pk_fma_f32 v[20:21], v[154:155], v[20:21], v[140:141]
	s_waitcnt vmcnt(3)
; __device__ __forceinline__ unsigned cvt_pk_bf16(float lo, float hi) { const f32x2 v = {lo, hi}; const bf16x2_t b = __builtin_convertvector(v, bf16x2_t); return __builtin_bit_cast(unsigned, b); }
;     __device__ __forceinline__ void fused(f32x4 (&acc)[2][2][4][2], const Unit& u, int wr, int wc, int fr, int fq, LAS unsigned char* lds, int wid, int lane) const {
;     ...
; #pragma unroll
;             for (int ai = 0; ai < 2; ++ai)
; #pragma unroll
;                 for (int m = 0; m < 4; ++m) {
;                     const int r = ai * 128 + wr * 64 + m * 16 + fr; const float rinv = S[r];
;                     const size_t off = (size_t)(u.pm * 256 + r) * DM + col0;
; #pragma unroll
;                     for (int bj = 0; bj < 2; ++bj)
; #pragma unroll
;                         for (int n = 0; n < 2; ++n) {
;                             const f32x4 y = acc[ai][bj][m][n] * rinv * Av[bj][n] + Bv[bj][n];
;                             if (mode == 0) { u32x2 w; w.x = cvt_pk_bf16(y[0], y[1]); w.y = cvt_pk_bf16(y[2], y[3]); *(u32x2*)(H + off + bj * 128 + n * 16) = w; }
;                             else *(f32x4*)(Fout + off + bj * 128 + n * 16) = y;
;                         }
	v_pk_fma_f32 v[116:117], v[160:161], v[116:117], v[144:145]
	v_pk_fma_f32 v[114:115], v[162:163], v[114:115], v[142:143]
	s_nop 0
	v_cvt_pk_bf16_f32 v114, v114, v115
	v_cvt_pk_bf16_f32 v115, v116, v117
	global_store_dwordx2 v[128:129], v[114:115], off offset:288
	v_add_u32_e32 v114, 16, v164
	v_ashrrev_i32_e32 v115, 31, v114
	v_lshlrev_b64 v[112:113], 12, v[114:115]
	v_lshl_add_u64 v[112:113], s[0:1], 0, v[112:113]
	v_lshl_add_u64 v[112:113], v[112:113], 0, v[126:127]
	global_store_dwordx2 v[112:113], v[18:19], off offset:32
	v_pk_mul_f32 v[18:19], v[22:23], v[0:1] op_sel_hi:[1,0]
	global_store_dwordx2 v[112:113], v[110:111], off
	v_pk_fma_f32 v[18:19], v[156:157], v[18:19], v[138:139]
	s_nop 0
	v_cvt_pk_bf16_f32 v18, v18, v19
	v_cvt_pk_bf16_f32 v19, v20, v21
	global_store_dwordx2 v[112:113], v[18:19], off offset:256
	v_pk_mul_f32 v[18:19], v[42:43], v[0:1] op_sel_hi:[1,0]
	v_pk_mul_f32 v[20:21], v[44:45], v[0:1] op_sel_hi:[1,0]
	v_pk_fma_f32 v[18:19], v[162:163], v[18:19], v[142:143]
	v_pk_fma_f32 v[20:21], v[160:161], v[20:21], v[144:145]
	v_cvt_pk_bf16_f32 v18, v18, v19
	v_cvt_pk_bf16_f32 v19, v20, v21
	global_store_dwordx2 v[112:113], v[18:19], off offset:288
	ds_read2_b32 v[18:19], v168 offset0:32 offset1:48
	v_add_u32_e32 v20, 32, v164
	v_ashrrev_i32_e32 v21, 31, v20
	v_lshlrev_b64 v[20:21], 12, v[20:21]
	v_lshl_add_u64 v[20:21], s[0:1], 0, v[20:21]
	s_waitcnt lgkmcnt(0)
	v_pk_mul_f32 v[22:23], v[38:39], v[18:19] op_sel_hi:[1,0]
	v_pk_mul_f32 v[24:25], v[40:41], v[18:19] op_sel_hi:[1,0]
	v_pk_fma_f32 v[22:23], v[148:149], v[22:23], v[130:131]
	v_pk_fma_f32 v[24:25], v[146:147], v[24:25], v[132:133]
	v_cvt_pk_bf16_f32 v22, v22, v23
	v_cvt_pk_bf16_f32 v23, v24, v25
	v_lshl_add_u64 v[20:21], v[20:21], 0, v[126:127]
	global_store_dwordx2 v[20:21], v[22:23], off
	v_pk_mul_f32 v[22:23], v[26:27], v[18:19] op_sel_hi:[1,0]
	v_pk_mul_f32 v[24:25], v[28:29], v[18:19] op_sel_hi:[1,0]
	v_pk_fma_f32 v[22:23], v[152:153], v[22:23], v[134:135]
	v_pk_fma_f32 v[24:25], v[150:151], v[24:25], v[136:137]
	v_cvt_pk_bf16_f32 v22, v22, v23
	v_cvt_pk_bf16_f32 v23, v24, v25
	global_store_dwordx2 v[20:21], v[22:23], off offset:32
	v_pk_mul_f32 v[22:23], v[30:31], v[18:19] op_sel_hi:[1,0]
	v_pk_mul_f32 v[24:25], v[32:33], v[18:19] op_sel_hi:[1,0]
	v_pk_fma_f32 v[22:23], v[156:157], v[22:23], v[138:139]
	v_pk_fma_f32 v[24:25], v[154:155], v[24:25], v[140:141]
	v_cvt_pk_bf16_f32 v22, v22, v23
	v_cvt_pk_bf16_f32 v23, v24, v25
	global_store_dwordx2 v[20:21], v[22:23], off offset:256
	v_pk_mul_f32 v[22:23], v[34:35], v[18:19] op_sel_hi:[1,0]
	v_pk_mul_f32 v[24:25], v[36:37], v[18:19] op_sel_hi:[1,0]
	v_pk_fma_f32 v[22:23], v[162:163], v[22:23], v[142:143]
	v_pk_fma_f32 v[24:25], v[160:161], v[24:25], v[144:145]
	v_cvt_pk_bf16_f32 v22, v22, v23
	v_cvt_pk_bf16_f32 v23, v24, v25
	v_mov_b32_e32 v0, v19
	global_store_dwordx2 v[20:21], v[22:23], off offset:288
	v_add_u32_e32 v20, 48, v164
	v_pk_mul_f32 v[14:15], v[14:15], v[0:1] op_sel_hi:[1,0]
	v_pk_mul_f32 v[16:17], v[16:17], v[0:1] op_sel_hi:[1,0]
	v_ashrrev_i32_e32 v21, 31, v20
	v_pk_fma_f32 v[16:17], v[146:147], v[16:17], v[132:133]
	v_pk_fma_f32 v[14:15], v[148:149], v[14:15], v[130:131]
	v_pk_mul_f32 v[2:3], v[2:3], v[0:1] op_sel_hi:[1,0]
	v_cvt_pk_bf16_f32 v14, v14, v15
	v_cvt_pk_bf16_f32 v15, v16, v17
	v_lshlrev_b64 v[16:17], 12, v[20:21]
	v_pk_mul_f32 v[4:5], v[4:5], v[0:1] op_sel_hi:[1,0]
	v_lshl_add_u64 v[16:17], s[0:1], 0, v[16:17]
	v_pk_fma_f32 v[4:5], v[150:151], v[4:5], v[136:137]
	v_pk_fma_f32 v[2:3], v[152:153], v[2:3], v[134:135]
	v_lshl_add_u64 v[16:17], v[16:17], 0, v[126:127]
	v_cvt_pk_bf16_f32 v2, v2, v3
	v_cvt_pk_bf16_f32 v3, v4, v5
	global_store_dwordx2 v[16:17], v[2:3], off offset:32
	v_pk_mul_f32 v[2:3], v[6:7], v[0:1] op_sel_hi:[1,0]
	v_pk_mul_f32 v[4:5], v[8:9], v[0:1] op_sel_hi:[1,0]
	v_pk_fma_f32 v[2:3], v[156:157], v[2:3], v[138:139]
	v_pk_fma_f32 v[4:5], v[154:155], v[4:5], v[140:141]
	v_cvt_pk_bf16_f32 v2, v2, v3
	v_cvt_pk_bf16_f32 v3, v4, v5
	global_store_dwordx2 v[16:17], v[2:3], off offset:256
	v_pk_mul_f32 v[2:3], v[10:11], v[0:1] op_sel_hi:[1,0]
	v_pk_mul_f32 v[4:5], v[12:13], v[0:1] op_sel_hi:[1,0]
	v_pk_fma_f32 v[2:3], v[162:163], v[2:3], v[142:143]
	v_pk_fma_f32 v[4:5], v[160:161], v[4:5], v[144:145]
	v_cvt_pk_bf16_f32 v2, v2, v3
	v_cvt_pk_bf16_f32 v3, v4, v5
	global_store_dwordx2 v[16:17], v[2:3], off offset:288
	ds_read2_b32 v[2:3], v168 offset0:128 offset1:144
	v_add_u32_e32 v4, 0x80, v164
	v_ashrrev_i32_e32 v5, 31, v4
	v_lshlrev_b64 v[4:5], 12, v[4:5]
	v_lshl_add_u64 v[4:5], s[0:1], 0, v[4:5]
	s_waitcnt lgkmcnt(0)
; __device__ __forceinline__ unsigned cvt_pk_bf16(float lo, float hi) { const f32x2 v = {lo, hi}; const bf16x2_t b = __builtin_convertvector(v, bf16x2_t); return __builtin_bit_cast(unsigned, b); }
;     __device__ __forceinline__ void fused(f32x4 (&acc)[2][2][4][2], const Unit& u, int wr, int wc, int fr, int fq, LAS unsigned char* lds, int wid, int lane) const {
;     ...
; #pragma unroll
;             for (int ai = 0; ai < 2; ++ai)
; #pragma unroll
;                 for (int m = 0; m < 4; ++m) {
;                     const int r = ai * 128 + wr * 64 + m * 16 + fr; const float rinv = S[r];
;                     const size_t off = (size_t)(u.pm * 256 + r) * DM + col0;
; #pragma unroll
;                     for (int bj = 0; bj < 2; ++bj)
; #pragma unroll
;                         for (int n = 0; n < 2; ++n) {
;                             const f32x4 y = acc[ai][bj][m][n] * rinv * Av[bj][n] + Bv[bj][n];
;                             if (mode == 0) { u32x2 w; w.x = cvt_pk_bf16(y[0], y[1]); w.y = cvt_pk_bf16(y[2], y[3]); *(u32x2*)(H + off + bj * 128 + n * 16) = w; }
;                             else *(f32x4*)(Fout + off + bj * 128 + n * 16) = y;
;                         }
	v_pk_mul_f32 v[6:7], v[106:107], v[2:3] op_sel_hi:[1,0]
	v_pk_mul_f32 v[8:9], v[108:109], v[2:3] op_sel_hi:[1,0]
	v_pk_fma_f32 v[6:7], v[148:149], v[6:7], v[130:131]
	v_pk_fma_f32 v[8:9], v[146:147], v[8:9], v[132:133]
	v_cvt_pk_bf16_f32 v6, v6, v7
	v_cvt_pk_bf16_f32 v7, v8, v9
	v_lshl_add_u64 v[4:5], v[4:5], 0, v[126:127]
	global_store_dwordx2 v[4:5], v[6:7], off
	v_pk_mul_f32 v[6:7], v[102:103], v[2:3] op_sel_hi:[1,0]
	v_pk_mul_f32 v[8:9], v[104:105], v[2:3] op_sel_hi:[1,0]
	v_pk_fma_f32 v[6:7], v[152:153], v[6:7], v[134:135]
	v_pk_fma_f32 v[8:9], v[150:151], v[8:9], v[136:137]
	v_cvt_pk_bf16_f32 v6, v6, v7
	v_cvt_pk_bf16_f32 v7, v8, v9
	global_store_dwordx2 v[4:5], v[6:7], off offset:32
	v_pk_mul_f32 v[6:7], v[98:99], v[2:3] op_sel_hi:[1,0]
	v_pk_mul_f32 v[8:9], v[100:101], v[2:3] op_sel_hi:[1,0]
	v_pk_fma_f32 v[6:7], v[156:157], v[6:7], v[138:139]
	v_pk_fma_f32 v[8:9], v[154:155], v[8:9], v[140:141]
	v_cvt_pk_bf16_f32 v6, v6, v7
	v_cvt_pk_bf16_f32 v7, v8, v9
	global_store_dwordx2 v[4:5], v[6:7], off offset:256
	v_pk_mul_f32 v[6:7], v[86:87], v[2:3] op_sel_hi:[1,0]
	v_pk_mul_f32 v[8:9], v[88:89], v[2:3] op_sel_hi:[1,0]
	v_pk_fma_f32 v[6:7], v[162:163], v[6:7], v[142:143]
	v_pk_fma_f32 v[8:9], v[160:161], v[8:9], v[144:145]
	v_cvt_pk_bf16_f32 v6, v6, v7
	v_cvt_pk_bf16_f32 v7, v8, v9
	global_store_dwordx2 v[4:5], v[6:7], off offset:288
	v_add_u32_e32 v4, 0x90, v164
	v_ashrrev_i32_e32 v5, 31, v4
	v_mov_b32_e32 v0, v3
	v_pk_mul_f32 v[2:3], v[78:79], v[0:1] op_sel_hi:[1,0]
	v_pk_mul_f32 v[6:7], v[80:81], v[0:1] op_sel_hi:[1,0]
	v_lshlrev_b64 v[4:5], 12, v[4:5]
	v_pk_fma_f32 v[6:7], v[146:147], v[6:7], v[132:133]
	v_pk_fma_f32 v[2:3], v[148:149], v[2:3], v[130:131]
	v_lshl_add_u64 v[4:5], s[0:1], 0, v[4:5]
	v_cvt_pk_bf16_f32 v2, v2, v3
	v_cvt_pk_bf16_f32 v3, v6, v7
	v_lshl_add_u64 v[4:5], v[4:5], 0, v[126:127]
	global_store_dwordx2 v[4:5], v[2:3], off
	v_pk_mul_f32 v[2:3], v[82:83], v[0:1] op_sel_hi:[1,0]
	v_pk_mul_f32 v[6:7], v[84:85], v[0:1] op_sel_hi:[1,0]
	v_pk_fma_f32 v[2:3], v[152:153], v[2:3], v[134:135]
	v_pk_fma_f32 v[6:7], v[150:151], v[6:7], v[136:137]
	v_cvt_pk_bf16_f32 v2, v2, v3
	v_cvt_pk_bf16_f32 v3, v6, v7
	global_store_dwordx2 v[4:5], v[2:3], off offset:32
	v_pk_mul_f32 v[2:3], v[90:91], v[0:1] op_sel_hi:[1,0]
	v_pk_mul_f32 v[6:7], v[92:93], v[0:1] op_sel_hi:[1,0]
	v_pk_fma_f32 v[2:3], v[156:157], v[2:3], v[138:139]
	v_pk_fma_f32 v[6:7], v[154:155], v[6:7], v[140:141]
	v_cvt_pk_bf16_f32 v2, v2, v3
	v_cvt_pk_bf16_f32 v3, v6, v7
	global_store_dwordx2 v[4:5], v[2:3], off offset:256
	v_pk_mul_f32 v[2:3], v[94:95], v[0:1] op_sel_hi:[1,0]
	v_pk_mul_f32 v[6:7], v[96:97], v[0:1] op_sel_hi:[1,0]
	v_pk_fma_f32 v[2:3], v[162:163], v[2:3], v[142:143]
	v_pk_fma_f32 v[6:7], v[160:161], v[6:7], v[144:145]
	v_cvt_pk_bf16_f32 v2, v2, v3
	v_cvt_pk_bf16_f32 v3, v6, v7
	global_store_dwordx2 v[4:5], v[2:3], off offset:288
	ds_read2_b32 v[2:3], v168 offset0:160 offset1:176
	v_add_u32_e32 v4, 0xa0, v164
	v_ashrrev_i32_e32 v5, 31, v4
	v_lshlrev_b64 v[4:5], 12, v[4:5]
	v_lshl_add_u64 v[4:5], s[0:1], 0, v[4:5]
	s_waitcnt lgkmcnt(0)
	v_pk_mul_f32 v[6:7], v[74:75], v[2:3] op_sel_hi:[1,0]
	v_pk_mul_f32 v[8:9], v[76:77], v[2:3] op_sel_hi:[1,0]
	v_pk_fma_f32 v[6:7], v[148:149], v[6:7], v[130:131]
	v_pk_fma_f32 v[8:9], v[146:147], v[8:9], v[132:133]
	v_cvt_pk_bf16_f32 v6, v6, v7
	v_cvt_pk_bf16_f32 v7, v8, v9
	v_lshl_add_u64 v[4:5], v[4:5], 0, v[126:127]
	global_store_dwordx2 v[4:5], v[6:7], off
	v_pk_mul_f32 v[6:7], v[62:63], v[2:3] op_sel_hi:[1,0]
	v_pk_mul_f32 v[8:9], v[64:65], v[2:3] op_sel_hi:[1,0]
	v_pk_fma_f32 v[6:7], v[152:153], v[6:7], v[134:135]
	v_pk_fma_f32 v[8:9], v[150:151], v[8:9], v[136:137]
	v_cvt_pk_bf16_f32 v6, v6, v7
	v_cvt_pk_bf16_f32 v7, v8, v9
	global_store_dwordx2 v[4:5], v[6:7], off offset:32
	v_pk_mul_f32 v[6:7], v[66:67], v[2:3] op_sel_hi:[1,0]
	v_pk_mul_f32 v[8:9], v[68:69], v[2:3] op_sel_hi:[1,0]
	v_pk_fma_f32 v[6:7], v[156:157], v[6:7], v[138:139]
	v_pk_fma_f32 v[8:9], v[154:155], v[8:9], v[140:141]
	v_cvt_pk_bf16_f32 v6, v6, v7
	v_cvt_pk_bf16_f32 v7, v8, v9
	global_store_dwordx2 v[4:5], v[6:7], off offset:256
	v_pk_mul_f32 v[6:7], v[70:71], v[2:3] op_sel_hi:[1,0]
	v_pk_mul_f32 v[8:9], v[72:73], v[2:3] op_sel_hi:[1,0]
	v_pk_fma_f32 v[6:7], v[162:163], v[6:7], v[142:143]
	v_pk_fma_f32 v[8:9], v[160:161], v[8:9], v[144:145]
	v_cvt_pk_bf16_f32 v6, v6, v7
	v_cvt_pk_bf16_f32 v7, v8, v9
	global_store_dwordx2 v[4:5], v[6:7], off offset:288
	v_add_u32_e32 v4, 0xb0, v164
	v_ashrrev_i32_e32 v5, 31, v4
	v_mov_b32_e32 v0, v3
	v_pk_mul_f32 v[2:3], v[58:59], v[0:1] op_sel_hi:[1,0]
	v_pk_mul_f32 v[6:7], v[60:61], v[0:1] op_sel_hi:[1,0]
	v_lshlrev_b64 v[4:5], 12, v[4:5]
	v_pk_fma_f32 v[6:7], v[146:147], v[6:7], v[132:133]
	v_pk_fma_f32 v[2:3], v[148:149], v[2:3], v[130:131]
	v_lshl_add_u64 v[4:5], s[0:1], 0, v[4:5]
	v_cvt_pk_bf16_f32 v2, v2, v3
	v_cvt_pk_bf16_f32 v3, v6, v7
	v_lshl_add_u64 v[4:5], v[4:5], 0, v[126:127]
	global_store_dwordx2 v[16:17], v[14:15], off
	global_store_dwordx2 v[4:5], v[2:3], off
	v_pk_mul_f32 v[2:3], v[46:47], v[0:1] op_sel_hi:[1,0]
	v_pk_mul_f32 v[6:7], v[48:49], v[0:1] op_sel_hi:[1,0]
	v_pk_fma_f32 v[2:3], v[152:153], v[2:3], v[134:135]
	v_pk_fma_f32 v[6:7], v[150:151], v[6:7], v[136:137]
	v_cvt_pk_bf16_f32 v2, v2, v3
	v_cvt_pk_bf16_f32 v3, v6, v7
	global_store_dwordx2 v[4:5], v[2:3], off offset:32
	v_pk_mul_f32 v[2:3], v[50:51], v[0:1] op_sel_hi:[1,0]
	v_pk_mul_f32 v[6:7], v[52:53], v[0:1] op_sel_hi:[1,0]
	v_pk_fma_f32 v[2:3], v[156:157], v[2:3], v[138:139]
	v_pk_fma_f32 v[6:7], v[154:155], v[6:7], v[140:141]
	v_cvt_pk_bf16_f32 v2, v2, v3
	v_cvt_pk_bf16_f32 v3, v6, v7
	global_store_dwordx2 v[4:5], v[2:3], off offset:256
	v_pk_mul_f32 v[2:3], v[54:55], v[0:1] op_sel_hi:[1,0]
	v_pk_mul_f32 v[6:7], v[56:57], v[0:1] op_sel_hi:[1,0]
	v_pk_fma_f32 v[2:3], v[162:163], v[2:3], v[142:143]
	v_pk_fma_f32 v[6:7], v[160:161], v[6:7], v[144:145]
	v_cvt_pk_bf16_f32 v2, v2, v3
	v_cvt_pk_bf16_f32 v3, v6, v7
	global_store_dwordx2 v[4:5], v[2:3], off offset:288
